# adds batched phase-3 segment scan (16 state/decay loads in flight instead of serialized round trips)
# speedup vs baseline: 1.0934x; 1.0019x over previous
.LBB0_261:
	s_load_dwordx2 s[90:91], s[0:1], 0x118
	v_lshrrev_b32_e32 v10, 13, v8
	v_and_b32_e32 v11, 0x1fff, v8
	v_lshlrev_b32_e32 v12, 21, v10
	v_lshl_add_u32 v12, v11, 4, v12
	v_and_b32_e32 v13, 31, v8
	v_lshlrev_b32_e32 v14, 13, v10
	v_lshl_add_u32 v13, v13, 4, v14
	s_mov_b64 s[92:93], s[16:17]
	s_mov_b64 s[98:99], s[16:17]
	s_waitcnt lgkmcnt(0)
	s_mov_b64 s[96:97], s[90:91]
	global_load_dwordx4 v[16:19], v12, s[92:93]
	global_load_dwordx4 v[80:83], v13, s[96:97]
	s_add_u32 s92, s92, 0x20000
	s_addc_u32 s93, s93, 0
	s_add_u32 s96, s96, 0x200
	s_addc_u32 s97, s97, 0
	global_load_dwordx4 v[20:23], v12, s[92:93]
	global_load_dwordx4 v[84:87], v13, s[96:97]
	s_add_u32 s92, s92, 0x20000
	s_addc_u32 s93, s93, 0
	s_add_u32 s96, s96, 0x200
	s_addc_u32 s97, s97, 0
	global_load_dwordx4 v[24:27], v12, s[92:93]
	global_load_dwordx4 v[88:91], v13, s[96:97]
	s_add_u32 s92, s92, 0x20000
	s_addc_u32 s93, s93, 0
	s_add_u32 s96, s96, 0x200
	s_addc_u32 s97, s97, 0
	global_load_dwordx4 v[28:31], v12, s[92:93]
	global_load_dwordx4 v[92:95], v13, s[96:97]
	s_add_u32 s92, s92, 0x20000
	s_addc_u32 s93, s93, 0
	s_add_u32 s96, s96, 0x200
	s_addc_u32 s97, s97, 0
	global_load_dwordx4 v[32:35], v12, s[92:93]
	global_load_dwordx4 v[96:99], v13, s[96:97]
	s_add_u32 s92, s92, 0x20000
	s_addc_u32 s93, s93, 0
	s_add_u32 s96, s96, 0x200
	s_addc_u32 s97, s97, 0
	global_load_dwordx4 v[36:39], v12, s[92:93]
	global_load_dwordx4 v[100:103], v13, s[96:97]
	s_add_u32 s92, s92, 0x20000
	s_addc_u32 s93, s93, 0
	s_add_u32 s96, s96, 0x200
	s_addc_u32 s97, s97, 0
	global_load_dwordx4 v[40:43], v12, s[92:93]
	global_load_dwordx4 v[104:107], v13, s[96:97]
	s_add_u32 s92, s92, 0x20000
	s_addc_u32 s93, s93, 0
	s_add_u32 s96, s96, 0x200
	s_addc_u32 s97, s97, 0
	global_load_dwordx4 v[44:47], v12, s[92:93]
	global_load_dwordx4 v[108:111], v13, s[96:97]
	s_add_u32 s92, s92, 0x20000
	s_addc_u32 s93, s93, 0
	s_add_u32 s96, s96, 0x200
	s_addc_u32 s97, s97, 0
	global_load_dwordx4 v[48:51], v12, s[92:93]
	global_load_dwordx4 v[112:115], v13, s[96:97]
	s_add_u32 s92, s92, 0x20000
	s_addc_u32 s93, s93, 0
	s_add_u32 s96, s96, 0x200
	s_addc_u32 s97, s97, 0
	global_load_dwordx4 v[52:55], v12, s[92:93]
	global_load_dwordx4 v[116:119], v13, s[96:97]
	s_add_u32 s92, s92, 0x20000
	s_addc_u32 s93, s93, 0
	s_add_u32 s96, s96, 0x200
	s_addc_u32 s97, s97, 0
	global_load_dwordx4 v[56:59], v12, s[92:93]
	global_load_dwordx4 v[120:123], v13, s[96:97]
	s_add_u32 s92, s92, 0x20000
	s_addc_u32 s93, s93, 0
	s_add_u32 s96, s96, 0x200
	s_addc_u32 s97, s97, 0
	global_load_dwordx4 v[60:63], v12, s[92:93]
	global_load_dwordx4 v[124:127], v13, s[96:97]
	s_add_u32 s92, s92, 0x20000
	s_addc_u32 s93, s93, 0
	s_add_u32 s96, s96, 0x200
	s_addc_u32 s97, s97, 0
	global_load_dwordx4 v[64:67], v12, s[92:93]
	global_load_dwordx4 v[128:131], v13, s[96:97]
	s_add_u32 s92, s92, 0x20000
	s_addc_u32 s93, s93, 0
	s_add_u32 s96, s96, 0x200
	s_addc_u32 s97, s97, 0
	global_load_dwordx4 v[68:71], v12, s[92:93]
	global_load_dwordx4 v[132:135], v13, s[96:97]
	s_add_u32 s92, s92, 0x20000
	s_addc_u32 s93, s93, 0
	s_add_u32 s96, s96, 0x200
	s_addc_u32 s97, s97, 0
	global_load_dwordx4 v[72:75], v12, s[92:93]
	global_load_dwordx4 v[136:139], v13, s[96:97]
	s_add_u32 s92, s92, 0x20000
	s_addc_u32 s93, s93, 0
	s_add_u32 s96, s96, 0x200
	s_addc_u32 s97, s97, 0
	global_load_dwordx4 v[76:79], v12, s[92:93]
	global_load_dwordx4 v[140:143], v13, s[96:97]
	v_mov_b32_e32 v148, 0
	v_mov_b32_e32 v149, 0
	v_mov_b32_e32 v150, 0
	v_mov_b32_e32 v151, 0
	s_waitcnt vmcnt(30)
	global_store_dwordx4 v12, v[148:151], s[98:99]
	v_fma_f32 v16, v148, v80, v16
	v_fma_f32 v17, v149, v81, v17
	v_fma_f32 v18, v150, v82, v18
	v_fma_f32 v19, v151, v83, v19
	s_add_u32 s98, s98, 0x20000
	s_addc_u32 s99, s99, 0
	s_waitcnt vmcnt(29)
	global_store_dwordx4 v12, v[16:19], s[98:99]
	v_fma_f32 v20, v16, v84, v20
	v_fma_f32 v21, v17, v85, v21
	v_fma_f32 v22, v18, v86, v22
	v_fma_f32 v23, v19, v87, v23
	s_add_u32 s98, s98, 0x20000
	s_addc_u32 s99, s99, 0
	s_waitcnt vmcnt(28)
	global_store_dwordx4 v12, v[20:23], s[98:99]
	v_fma_f32 v24, v20, v88, v24
	v_fma_f32 v25, v21, v89, v25
	v_fma_f32 v26, v22, v90, v26
	v_fma_f32 v27, v23, v91, v27
	s_add_u32 s98, s98, 0x20000
	s_addc_u32 s99, s99, 0
	s_waitcnt vmcnt(27)
	global_store_dwordx4 v12, v[24:27], s[98:99]
	v_fma_f32 v28, v24, v92, v28
	v_fma_f32 v29, v25, v93, v29
	v_fma_f32 v30, v26, v94, v30
	v_fma_f32 v31, v27, v95, v31
	s_add_u32 s98, s98, 0x20000
	s_addc_u32 s99, s99, 0
	s_waitcnt vmcnt(26)
	global_store_dwordx4 v12, v[28:31], s[98:99]
	v_fma_f32 v32, v28, v96, v32
	v_fma_f32 v33, v29, v97, v33
	v_fma_f32 v34, v30, v98, v34
	v_fma_f32 v35, v31, v99, v35
	s_add_u32 s98, s98, 0x20000
	s_addc_u32 s99, s99, 0
	s_waitcnt vmcnt(25)
	global_store_dwordx4 v12, v[32:35], s[98:99]
	v_fma_f32 v36, v32, v100, v36
	v_fma_f32 v37, v33, v101, v37
	v_fma_f32 v38, v34, v102, v38
	v_fma_f32 v39, v35, v103, v39
	s_add_u32 s98, s98, 0x20000
	s_addc_u32 s99, s99, 0
	s_waitcnt vmcnt(24)
	global_store_dwordx4 v12, v[36:39], s[98:99]
	v_fma_f32 v40, v36, v104, v40
	v_fma_f32 v41, v37, v105, v41
	v_fma_f32 v42, v38, v106, v42
	v_fma_f32 v43, v39, v107, v43
	s_add_u32 s98, s98, 0x20000
	s_addc_u32 s99, s99, 0
	s_waitcnt vmcnt(23)
	global_store_dwordx4 v12, v[40:43], s[98:99]
	v_fma_f32 v44, v40, v108, v44
	v_fma_f32 v45, v41, v109, v45
	v_fma_f32 v46, v42, v110, v46
	v_fma_f32 v47, v43, v111, v47
	s_add_u32 s98, s98, 0x20000
	s_addc_u32 s99, s99, 0
	s_waitcnt vmcnt(22)
	global_store_dwordx4 v12, v[44:47], s[98:99]
	v_fma_f32 v48, v44, v112, v48
	v_fma_f32 v49, v45, v113, v49
	v_fma_f32 v50, v46, v114, v50
	v_fma_f32 v51, v47, v115, v51
	s_add_u32 s98, s98, 0x20000
	s_addc_u32 s99, s99, 0
	s_waitcnt vmcnt(21)
	global_store_dwordx4 v12, v[48:51], s[98:99]
	v_fma_f32 v52, v48, v116, v52
	v_fma_f32 v53, v49, v117, v53
	v_fma_f32 v54, v50, v118, v54
	v_fma_f32 v55, v51, v119, v55
	s_add_u32 s98, s98, 0x20000
	s_addc_u32 s99, s99, 0
	s_waitcnt vmcnt(20)
	global_store_dwordx4 v12, v[52:55], s[98:99]
	v_fma_f32 v56, v52, v120, v56
	v_fma_f32 v57, v53, v121, v57
	v_fma_f32 v58, v54, v122, v58
	v_fma_f32 v59, v55, v123, v59
	s_add_u32 s98, s98, 0x20000
	s_addc_u32 s99, s99, 0
	s_waitcnt vmcnt(19)
	global_store_dwordx4 v12, v[56:59], s[98:99]
	v_fma_f32 v60, v56, v124, v60
	v_fma_f32 v61, v57, v125, v61
	v_fma_f32 v62, v58, v126, v62
	v_fma_f32 v63, v59, v127, v63
	s_add_u32 s98, s98, 0x20000
	s_addc_u32 s99, s99, 0
	s_waitcnt vmcnt(18)
	global_store_dwordx4 v12, v[60:63], s[98:99]
	v_fma_f32 v64, v60, v128, v64
	v_fma_f32 v65, v61, v129, v65
	v_fma_f32 v66, v62, v130, v66
	v_fma_f32 v67, v63, v131, v67
	s_add_u32 s98, s98, 0x20000
	s_addc_u32 s99, s99, 0
	s_waitcnt vmcnt(17)
	global_store_dwordx4 v12, v[64:67], s[98:99]
	v_fma_f32 v68, v64, v132, v68
	v_fma_f32 v69, v65, v133, v69
	v_fma_f32 v70, v66, v134, v70
	v_fma_f32 v71, v67, v135, v71
	s_add_u32 s98, s98, 0x20000
	s_addc_u32 s99, s99, 0
	s_waitcnt vmcnt(16)
	global_store_dwordx4 v12, v[68:71], s[98:99]
	v_fma_f32 v72, v68, v136, v72
	v_fma_f32 v73, v69, v137, v73
	v_fma_f32 v74, v70, v138, v74
	v_fma_f32 v75, v71, v139, v75
	s_add_u32 s98, s98, 0x20000
	s_addc_u32 s99, s99, 0
	s_waitcnt vmcnt(15)
	global_store_dwordx4 v12, v[72:75], s[98:99]
	v_add_u32_e32 v8, s26, v8
	v_cmp_lt_i32_e32 vcc, s34, v8
	s_or_b64 s[20:21], vcc, s[20:21]
	v_add_u32_e32 v9, s27, v9
	s_andn2_b64 exec, exec, s[20:21]
	s_cbranch_execnz .LBB0_261

.Lgp9_last:
	v_mfma_f32_16x16x32_bf16 v[0:3], v[232:235], v[192:195], v[0:3]
	v_mfma_f32_16x16x32_bf16 v[116:119], v[100:103], v[192:195], v[116:119]
	v_mfma_f32_16x16x32_bf16 v[4:7], v[236:239], v[192:195], v[4:7]
	v_mfma_f32_16x16x32_bf16 v[120:123], v[104:107], v[192:195], v[120:123]
	v_mfma_f32_16x16x32_bf16 v[8:11], v[240:243], v[192:195], v[8:11]
	v_mfma_f32_16x16x32_bf16 v[124:127], v[68:71], v[192:195], v[124:127]
	v_mfma_f32_16x16x32_bf16 v[12:15], v[244:247], v[192:195], v[12:15]
	v_mfma_f32_16x16x32_bf16 v[128:131], v[80:83], v[192:195], v[128:131]
	v_mfma_f32_16x16x32_bf16 v[16:19], v[232:235], v[204:207], v[16:19]
	v_mfma_f32_16x16x32_bf16 v[132:135], v[100:103], v[204:207], v[132:135]
	v_mfma_f32_16x16x32_bf16 v[20:23], v[236:239], v[204:207], v[20:23]
	v_mfma_f32_16x16x32_bf16 v[136:139], v[104:107], v[204:207], v[136:139]
	v_mfma_f32_16x16x32_bf16 v[24:27], v[240:243], v[204:207], v[24:27]
	v_mfma_f32_16x16x32_bf16 v[140:143], v[68:71], v[204:207], v[140:143]
	v_mfma_f32_16x16x32_bf16 v[28:31], v[244:247], v[204:207], v[28:31]
	v_mfma_f32_16x16x32_bf16 v[148:151], v[80:83], v[204:207], v[148:151]
	v_mfma_f32_16x16x32_bf16 v[32:35], v[232:235], v[208:211], v[32:35]
	v_mfma_f32_16x16x32_bf16 v[152:155], v[100:103], v[208:211], v[152:155]
	v_mfma_f32_16x16x32_bf16 v[36:39], v[236:239], v[208:211], v[36:39]
	v_mfma_f32_16x16x32_bf16 v[156:159], v[104:107], v[208:211], v[156:159]
	v_mfma_f32_16x16x32_bf16 v[40:43], v[240:243], v[208:211], v[40:43]
	v_mfma_f32_16x16x32_bf16 v[160:163], v[68:71], v[208:211], v[160:163]
	v_mfma_f32_16x16x32_bf16 v[44:47], v[244:247], v[208:211], v[44:47]
	v_mfma_f32_16x16x32_bf16 v[172:175], v[80:83], v[208:211], v[172:175]
	v_mfma_f32_16x16x32_bf16 v[48:51], v[232:235], v[212:215], v[48:51]
	v_mfma_f32_16x16x32_bf16 v[176:179], v[100:103], v[212:215], v[176:179]
	v_mfma_f32_16x16x32_bf16 v[52:55], v[236:239], v[212:215], v[52:55]
	v_mfma_f32_16x16x32_bf16 v[180:183], v[104:107], v[212:215], v[180:183]
	v_mfma_f32_16x16x32_bf16 v[56:59], v[240:243], v[212:215], v[56:59]
	v_mfma_f32_16x16x32_bf16 v[184:187], v[68:71], v[212:215], v[184:187]
	v_mfma_f32_16x16x32_bf16 v[60:63], v[244:247], v[212:215], v[60:63]
	v_mfma_f32_16x16x32_bf16 v[188:191], v[80:83], v[212:215], v[188:191]
	s_waitcnt lgkmcnt(0)
	v_mfma_f32_16x16x32_bf16 v[0:3], v[248:251], v[216:219], v[0:3]
	v_mfma_f32_16x16x32_bf16 v[116:119], v[200:203], v[216:219], v[116:119]
	v_mfma_f32_16x16x32_bf16 v[4:7], v[252:255], v[216:219], v[4:7]
	v_mfma_f32_16x16x32_bf16 v[120:123], v[164:167], v[216:219], v[120:123]
	v_mfma_f32_16x16x32_bf16 v[8:11], v[92:95], v[216:219], v[8:11]
	v_mfma_f32_16x16x32_bf16 v[124:127], v[112:115], v[216:219], v[124:127]
	v_mfma_f32_16x16x32_bf16 v[12:15], v[96:99], v[216:219], v[12:15]
	v_mfma_f32_16x16x32_bf16 v[128:131], v[76:79], v[216:219], v[128:131]
	v_mfma_f32_16x16x32_bf16 v[16:19], v[248:251], v[220:223], v[16:19]
	v_mfma_f32_16x16x32_bf16 v[132:135], v[200:203], v[220:223], v[132:135]
	v_mfma_f32_16x16x32_bf16 v[20:23], v[252:255], v[220:223], v[20:23]
	v_mfma_f32_16x16x32_bf16 v[136:139], v[164:167], v[220:223], v[136:139]
	v_mfma_f32_16x16x32_bf16 v[24:27], v[92:95], v[220:223], v[24:27]
	v_mfma_f32_16x16x32_bf16 v[140:143], v[112:115], v[220:223], v[140:143]
	v_mfma_f32_16x16x32_bf16 v[28:31], v[96:99], v[220:223], v[28:31]
	v_mfma_f32_16x16x32_bf16 v[148:151], v[76:79], v[220:223], v[148:151]
	v_mfma_f32_16x16x32_bf16 v[32:35], v[248:251], v[224:227], v[32:35]
	v_mfma_f32_16x16x32_bf16 v[152:155], v[200:203], v[224:227], v[152:155]
	v_mfma_f32_16x16x32_bf16 v[36:39], v[252:255], v[224:227], v[36:39]
	v_mfma_f32_16x16x32_bf16 v[156:159], v[164:167], v[224:227], v[156:159]
	v_mfma_f32_16x16x32_bf16 v[40:43], v[92:95], v[224:227], v[40:43]
	v_mfma_f32_16x16x32_bf16 v[160:163], v[112:115], v[224:227], v[160:163]
	v_mfma_f32_16x16x32_bf16 v[44:47], v[96:99], v[224:227], v[44:47]
	v_mfma_f32_16x16x32_bf16 v[172:175], v[76:79], v[224:227], v[172:175]
	v_mfma_f32_16x16x32_bf16 v[48:51], v[248:251], v[228:231], v[48:51]
	v_mfma_f32_16x16x32_bf16 v[176:179], v[200:203], v[228:231], v[176:179]
	v_mfma_f32_16x16x32_bf16 v[52:55], v[252:255], v[228:231], v[52:55]
	v_mfma_f32_16x16x32_bf16 v[180:183], v[164:167], v[228:231], v[180:183]
	v_mfma_f32_16x16x32_bf16 v[56:59], v[92:95], v[228:231], v[56:59]
	v_mfma_f32_16x16x32_bf16 v[184:187], v[112:115], v[228:231], v[184:187]
	v_mfma_f32_16x16x32_bf16 v[60:63], v[96:99], v[228:231], v[60:63]
	v_mfma_f32_16x16x32_bf16 v[188:191], v[76:79], v[228:231], v[188:191]
	s_nop 7
	s_nop 3
	s_load_dwordx2 s[84:85], s[0:1], 0xa0
	v_lshrrev_b32_e32 v220, 1, v168
	v_and_b32_e32 v220, 0x1c0, v220
	v_and_b32_e32 v221, 15, v168
	v_or_b32_e32 v220, v220, v221
	v_lshl_add_u32 v220, s50, 7, v220
	v_lshlrev_b32_e32 v220, 12, v220
	v_bfe_u32 v221, v168, 4, 2
	v_lshlrev_b32_e32 v217, 3, v221
	v_and_b32_e32 v221, 1, v221
	v_mul_u32_u24_e32 v221, 24, v221
	v_add3_u32 v220, v220, v221, v217
	v_bfe_u32 v221, v168, 6, 1
	s_lshl_b32 s87, s48, 8
	v_lshl_add_u32 v216, v221, 7, v220
	v_add_u32_e32 v216, s87, v216
	v_add_u32_e32 v217, 0x10000, v216
	v_add_u32_e32 v218, 0x20000, v216
	v_add_u32_e32 v219, 0x30000, v216
	s_waitcnt lgkmcnt(0)
	v_and_b32_sdwa v200, v0, v108 dst_sel:DWORD dst_unused:UNUSED_PAD src0_sel:WORD_1 src1_sel:DWORD
	v_and_b32_sdwa v201, v1, v108 dst_sel:DWORD dst_unused:UNUSED_PAD src0_sel:WORD_1 src1_sel:DWORD
	v_and_b32_sdwa v202, v2, v108 dst_sel:DWORD dst_unused:UNUSED_PAD src0_sel:WORD_1 src1_sel:DWORD
	v_and_b32_sdwa v203, v3, v108 dst_sel:DWORD dst_unused:UNUSED_PAD src0_sel:WORD_1 src1_sel:DWORD
	v_and_b32_sdwa v204, v4, v108 dst_sel:DWORD dst_unused:UNUSED_PAD src0_sel:WORD_1 src1_sel:DWORD
	v_and_b32_sdwa v205, v5, v108 dst_sel:DWORD dst_unused:UNUSED_PAD src0_sel:WORD_1 src1_sel:DWORD
	v_and_b32_sdwa v206, v6, v108 dst_sel:DWORD dst_unused:UNUSED_PAD src0_sel:WORD_1 src1_sel:DWORD
	v_and_b32_sdwa v207, v7, v108 dst_sel:DWORD dst_unused:UNUSED_PAD src0_sel:WORD_1 src1_sel:DWORD
	v_add3_u32 v192, v0, v200, s66
	v_add3_u32 v193, v1, v201, s66
	v_add3_u32 v194, v2, v202, s66
	v_add3_u32 v195, v3, v203, s66
	v_add3_u32 v196, v4, v204, s66
	v_add3_u32 v197, v5, v205, s66
	v_add3_u32 v198, v6, v206, s66
	v_add3_u32 v199, v7, v207, s66
	v_and_b32_e32 v193, 0xffff0000, v193
	v_and_b32_e32 v195, 0xffff0000, v195
	v_and_b32_e32 v197, 0xffff0000, v197
	v_and_b32_e32 v199, 0xffff0000, v199
	v_or_b32_sdwa v208, v193, v192 dst_sel:DWORD dst_unused:UNUSED_PAD src0_sel:DWORD src1_sel:WORD_1
	v_or_b32_sdwa v209, v195, v194 dst_sel:DWORD dst_unused:UNUSED_PAD src0_sel:DWORD src1_sel:WORD_1
	v_or_b32_sdwa v210, v197, v196 dst_sel:DWORD dst_unused:UNUSED_PAD src0_sel:DWORD src1_sel:WORD_1
	v_or_b32_sdwa v211, v199, v198 dst_sel:DWORD dst_unused:UNUSED_PAD src0_sel:DWORD src1_sel:WORD_1
	s_nop 1
	v_permlane16_swap_b32_e32 v208, v210
	v_permlane16_swap_b32_e32 v209, v211
	global_store_dwordx4 v216, v[208:211], s[84:85]
	v_and_b32_sdwa v200, v8, v108 dst_sel:DWORD dst_unused:UNUSED_PAD src0_sel:WORD_1 src1_sel:DWORD
	v_and_b32_sdwa v201, v9, v108 dst_sel:DWORD dst_unused:UNUSED_PAD src0_sel:WORD_1 src1_sel:DWORD
	v_and_b32_sdwa v202, v10, v108 dst_sel:DWORD dst_unused:UNUSED_PAD src0_sel:WORD_1 src1_sel:DWORD
	v_and_b32_sdwa v203, v11, v108 dst_sel:DWORD dst_unused:UNUSED_PAD src0_sel:WORD_1 src1_sel:DWORD
	v_and_b32_sdwa v204, v12, v108 dst_sel:DWORD dst_unused:UNUSED_PAD src0_sel:WORD_1 src1_sel:DWORD
	v_and_b32_sdwa v205, v13, v108 dst_sel:DWORD dst_unused:UNUSED_PAD src0_sel:WORD_1 src1_sel:DWORD
	v_and_b32_sdwa v206, v14, v108 dst_sel:DWORD dst_unused:UNUSED_PAD src0_sel:WORD_1 src1_sel:DWORD
	v_and_b32_sdwa v207, v15, v108 dst_sel:DWORD dst_unused:UNUSED_PAD src0_sel:WORD_1 src1_sel:DWORD
	v_add3_u32 v192, v8, v200, s66
	v_add3_u32 v193, v9, v201, s66
	v_add3_u32 v194, v10, v202, s66
	v_add3_u32 v195, v11, v203, s66
	v_add3_u32 v196, v12, v204, s66
	v_add3_u32 v197, v13, v205, s66
	v_add3_u32 v198, v14, v206, s66
	v_add3_u32 v199, v15, v207, s66
	v_and_b32_e32 v193, 0xffff0000, v193
	v_and_b32_e32 v195, 0xffff0000, v195
	v_and_b32_e32 v197, 0xffff0000, v197
	v_and_b32_e32 v199, 0xffff0000, v199
	v_or_b32_sdwa v212, v193, v192 dst_sel:DWORD dst_unused:UNUSED_PAD src0_sel:DWORD src1_sel:WORD_1
	v_or_b32_sdwa v213, v195, v194 dst_sel:DWORD dst_unused:UNUSED_PAD src0_sel:DWORD src1_sel:WORD_1
	v_or_b32_sdwa v214, v197, v196 dst_sel:DWORD dst_unused:UNUSED_PAD src0_sel:DWORD src1_sel:WORD_1
	v_or_b32_sdwa v215, v199, v198 dst_sel:DWORD dst_unused:UNUSED_PAD src0_sel:DWORD src1_sel:WORD_1
	s_nop 1
	v_permlane16_swap_b32_e32 v212, v214
	v_permlane16_swap_b32_e32 v213, v215
	global_store_dwordx4 v216, v[212:215], s[84:85] offset:64
	v_and_b32_sdwa v200, v16, v108 dst_sel:DWORD dst_unused:UNUSED_PAD src0_sel:WORD_1 src1_sel:DWORD
	v_and_b32_sdwa v201, v17, v108 dst_sel:DWORD dst_unused:UNUSED_PAD src0_sel:WORD_1 src1_sel:DWORD
	v_and_b32_sdwa v202, v18, v108 dst_sel:DWORD dst_unused:UNUSED_PAD src0_sel:WORD_1 src1_sel:DWORD
	v_and_b32_sdwa v203, v19, v108 dst_sel:DWORD dst_unused:UNUSED_PAD src0_sel:WORD_1 src1_sel:DWORD
	v_and_b32_sdwa v204, v20, v108 dst_sel:DWORD dst_unused:UNUSED_PAD src0_sel:WORD_1 src1_sel:DWORD
	v_and_b32_sdwa v205, v21, v108 dst_sel:DWORD dst_unused:UNUSED_PAD src0_sel:WORD_1 src1_sel:DWORD
	v_and_b32_sdwa v206, v22, v108 dst_sel:DWORD dst_unused:UNUSED_PAD src0_sel:WORD_1 src1_sel:DWORD
	v_and_b32_sdwa v207, v23, v108 dst_sel:DWORD dst_unused:UNUSED_PAD src0_sel:WORD_1 src1_sel:DWORD
	v_add3_u32 v192, v16, v200, s66
	v_add3_u32 v193, v17, v201, s66
	v_add3_u32 v194, v18, v202, s66
	v_add3_u32 v195, v19, v203, s66
	v_add3_u32 v196, v20, v204, s66
	v_add3_u32 v197, v21, v205, s66
	v_add3_u32 v198, v22, v206, s66
	v_add3_u32 v199, v23, v207, s66
	v_and_b32_e32 v193, 0xffff0000, v193
	v_and_b32_e32 v195, 0xffff0000, v195
	v_and_b32_e32 v197, 0xffff0000, v197
	v_and_b32_e32 v199, 0xffff0000, v199
	v_or_b32_sdwa v208, v193, v192 dst_sel:DWORD dst_unused:UNUSED_PAD src0_sel:DWORD src1_sel:WORD_1
	v_or_b32_sdwa v209, v195, v194 dst_sel:DWORD dst_unused:UNUSED_PAD src0_sel:DWORD src1_sel:WORD_1
	v_or_b32_sdwa v210, v197, v196 dst_sel:DWORD dst_unused:UNUSED_PAD src0_sel:DWORD src1_sel:WORD_1
	v_or_b32_sdwa v211, v199, v198 dst_sel:DWORD dst_unused:UNUSED_PAD src0_sel:DWORD src1_sel:WORD_1
	s_nop 1
	v_permlane16_swap_b32_e32 v208, v210
	v_permlane16_swap_b32_e32 v209, v211
	global_store_dwordx4 v217, v[208:211], s[84:85]
	v_and_b32_sdwa v200, v24, v108 dst_sel:DWORD dst_unused:UNUSED_PAD src0_sel:WORD_1 src1_sel:DWORD
	v_and_b32_sdwa v201, v25, v108 dst_sel:DWORD dst_unused:UNUSED_PAD src0_sel:WORD_1 src1_sel:DWORD
	v_and_b32_sdwa v202, v26, v108 dst_sel:DWORD dst_unused:UNUSED_PAD src0_sel:WORD_1 src1_sel:DWORD
	v_and_b32_sdwa v203, v27, v108 dst_sel:DWORD dst_unused:UNUSED_PAD src0_sel:WORD_1 src1_sel:DWORD
	v_and_b32_sdwa v204, v28, v108 dst_sel:DWORD dst_unused:UNUSED_PAD src0_sel:WORD_1 src1_sel:DWORD
	v_and_b32_sdwa v205, v29, v108 dst_sel:DWORD dst_unused:UNUSED_PAD src0_sel:WORD_1 src1_sel:DWORD
	v_and_b32_sdwa v206, v30, v108 dst_sel:DWORD dst_unused:UNUSED_PAD src0_sel:WORD_1 src1_sel:DWORD
	v_and_b32_sdwa v207, v31, v108 dst_sel:DWORD dst_unused:UNUSED_PAD src0_sel:WORD_1 src1_sel:DWORD
	v_add3_u32 v192, v24, v200, s66
	v_add3_u32 v193, v25, v201, s66
	v_add3_u32 v194, v26, v202, s66
	v_add3_u32 v195, v27, v203, s66
	v_add3_u32 v196, v28, v204, s66
	v_add3_u32 v197, v29, v205, s66
	v_add3_u32 v198, v30, v206, s66
	v_add3_u32 v199, v31, v207, s66
	v_and_b32_e32 v193, 0xffff0000, v193
	v_and_b32_e32 v195, 0xffff0000, v195
	v_and_b32_e32 v197, 0xffff0000, v197
	v_and_b32_e32 v199, 0xffff0000, v199
	v_or_b32_sdwa v212, v193, v192 dst_sel:DWORD dst_unused:UNUSED_PAD src0_sel:DWORD src1_sel:WORD_1
	v_or_b32_sdwa v213, v195, v194 dst_sel:DWORD dst_unused:UNUSED_PAD src0_sel:DWORD src1_sel:WORD_1
	v_or_b32_sdwa v214, v197, v196 dst_sel:DWORD dst_unused:UNUSED_PAD src0_sel:DWORD src1_sel:WORD_1
	v_or_b32_sdwa v215, v199, v198 dst_sel:DWORD dst_unused:UNUSED_PAD src0_sel:DWORD src1_sel:WORD_1
	s_nop 1
	v_permlane16_swap_b32_e32 v212, v214
	v_permlane16_swap_b32_e32 v213, v215
	global_store_dwordx4 v217, v[212:215], s[84:85] offset:64
	v_and_b32_sdwa v200, v32, v108 dst_sel:DWORD dst_unused:UNUSED_PAD src0_sel:WORD_1 src1_sel:DWORD
	v_and_b32_sdwa v201, v33, v108 dst_sel:DWORD dst_unused:UNUSED_PAD src0_sel:WORD_1 src1_sel:DWORD
	v_and_b32_sdwa v202, v34, v108 dst_sel:DWORD dst_unused:UNUSED_PAD src0_sel:WORD_1 src1_sel:DWORD
	v_and_b32_sdwa v203, v35, v108 dst_sel:DWORD dst_unused:UNUSED_PAD src0_sel:WORD_1 src1_sel:DWORD
	v_and_b32_sdwa v204, v36, v108 dst_sel:DWORD dst_unused:UNUSED_PAD src0_sel:WORD_1 src1_sel:DWORD
	v_and_b32_sdwa v205, v37, v108 dst_sel:DWORD dst_unused:UNUSED_PAD src0_sel:WORD_1 src1_sel:DWORD
	v_and_b32_sdwa v206, v38, v108 dst_sel:DWORD dst_unused:UNUSED_PAD src0_sel:WORD_1 src1_sel:DWORD
	v_and_b32_sdwa v207, v39, v108 dst_sel:DWORD dst_unused:UNUSED_PAD src0_sel:WORD_1 src1_sel:DWORD
	v_add3_u32 v192, v32, v200, s66
	v_add3_u32 v193, v33, v201, s66
	v_add3_u32 v194, v34, v202, s66
	v_add3_u32 v195, v35, v203, s66
	v_add3_u32 v196, v36, v204, s66
	v_add3_u32 v197, v37, v205, s66
	v_add3_u32 v198, v38, v206, s66
	v_add3_u32 v199, v39, v207, s66
	v_and_b32_e32 v193, 0xffff0000, v193
	v_and_b32_e32 v195, 0xffff0000, v195
	v_and_b32_e32 v197, 0xffff0000, v197
	v_and_b32_e32 v199, 0xffff0000, v199
	v_or_b32_sdwa v208, v193, v192 dst_sel:DWORD dst_unused:UNUSED_PAD src0_sel:DWORD src1_sel:WORD_1
	v_or_b32_sdwa v209, v195, v194 dst_sel:DWORD dst_unused:UNUSED_PAD src0_sel:DWORD src1_sel:WORD_1
	v_or_b32_sdwa v210, v197, v196 dst_sel:DWORD dst_unused:UNUSED_PAD src0_sel:DWORD src1_sel:WORD_1
	v_or_b32_sdwa v211, v199, v198 dst_sel:DWORD dst_unused:UNUSED_PAD src0_sel:DWORD src1_sel:WORD_1
	s_nop 1
	v_permlane16_swap_b32_e32 v208, v210
	v_permlane16_swap_b32_e32 v209, v211
	global_store_dwordx4 v218, v[208:211], s[84:85]
	v_and_b32_sdwa v200, v40, v108 dst_sel:DWORD dst_unused:UNUSED_PAD src0_sel:WORD_1 src1_sel:DWORD
	v_and_b32_sdwa v201, v41, v108 dst_sel:DWORD dst_unused:UNUSED_PAD src0_sel:WORD_1 src1_sel:DWORD
	v_and_b32_sdwa v202, v42, v108 dst_sel:DWORD dst_unused:UNUSED_PAD src0_sel:WORD_1 src1_sel:DWORD
	v_and_b32_sdwa v203, v43, v108 dst_sel:DWORD dst_unused:UNUSED_PAD src0_sel:WORD_1 src1_sel:DWORD
	v_and_b32_sdwa v204, v44, v108 dst_sel:DWORD dst_unused:UNUSED_PAD src0_sel:WORD_1 src1_sel:DWORD
	v_and_b32_sdwa v205, v45, v108 dst_sel:DWORD dst_unused:UNUSED_PAD src0_sel:WORD_1 src1_sel:DWORD
	v_and_b32_sdwa v206, v46, v108 dst_sel:DWORD dst_unused:UNUSED_PAD src0_sel:WORD_1 src1_sel:DWORD
	v_and_b32_sdwa v207, v47, v108 dst_sel:DWORD dst_unused:UNUSED_PAD src0_sel:WORD_1 src1_sel:DWORD
	v_add3_u32 v192, v40, v200, s66
	v_add3_u32 v193, v41, v201, s66
	v_add3_u32 v194, v42, v202, s66
	v_add3_u32 v195, v43, v203, s66
	v_add3_u32 v196, v44, v204, s66
	v_add3_u32 v197, v45, v205, s66
	v_add3_u32 v198, v46, v206, s66
	v_add3_u32 v199, v47, v207, s66
	v_and_b32_e32 v193, 0xffff0000, v193
	v_and_b32_e32 v195, 0xffff0000, v195
	v_and_b32_e32 v197, 0xffff0000, v197
	v_and_b32_e32 v199, 0xffff0000, v199
	v_or_b32_sdwa v212, v193, v192 dst_sel:DWORD dst_unused:UNUSED_PAD src0_sel:DWORD src1_sel:WORD_1
	v_or_b32_sdwa v213, v195, v194 dst_sel:DWORD dst_unused:UNUSED_PAD src0_sel:DWORD src1_sel:WORD_1
	v_or_b32_sdwa v214, v197, v196 dst_sel:DWORD dst_unused:UNUSED_PAD src0_sel:DWORD src1_sel:WORD_1
	v_or_b32_sdwa v215, v199, v198 dst_sel:DWORD dst_unused:UNUSED_PAD src0_sel:DWORD src1_sel:WORD_1
	s_nop 1
	v_permlane16_swap_b32_e32 v212, v214
	v_permlane16_swap_b32_e32 v213, v215
	global_store_dwordx4 v218, v[212:215], s[84:85] offset:64
	v_and_b32_sdwa v200, v48, v108 dst_sel:DWORD dst_unused:UNUSED_PAD src0_sel:WORD_1 src1_sel:DWORD
	v_and_b32_sdwa v201, v49, v108 dst_sel:DWORD dst_unused:UNUSED_PAD src0_sel:WORD_1 src1_sel:DWORD
	v_and_b32_sdwa v202, v50, v108 dst_sel:DWORD dst_unused:UNUSED_PAD src0_sel:WORD_1 src1_sel:DWORD
	v_and_b32_sdwa v203, v51, v108 dst_sel:DWORD dst_unused:UNUSED_PAD src0_sel:WORD_1 src1_sel:DWORD
	v_and_b32_sdwa v204, v52, v108 dst_sel:DWORD dst_unused:UNUSED_PAD src0_sel:WORD_1 src1_sel:DWORD
	v_and_b32_sdwa v205, v53, v108 dst_sel:DWORD dst_unused:UNUSED_PAD src0_sel:WORD_1 src1_sel:DWORD
	v_and_b32_sdwa v206, v54, v108 dst_sel:DWORD dst_unused:UNUSED_PAD src0_sel:WORD_1 src1_sel:DWORD
	v_and_b32_sdwa v207, v55, v108 dst_sel:DWORD dst_unused:UNUSED_PAD src0_sel:WORD_1 src1_sel:DWORD
	v_add3_u32 v192, v48, v200, s66
	v_add3_u32 v193, v49, v201, s66
	v_add3_u32 v194, v50, v202, s66
	v_add3_u32 v195, v51, v203, s66
	v_add3_u32 v196, v52, v204, s66
	v_add3_u32 v197, v53, v205, s66
	v_add3_u32 v198, v54, v206, s66
	v_add3_u32 v199, v55, v207, s66
	v_and_b32_e32 v193, 0xffff0000, v193
	v_and_b32_e32 v195, 0xffff0000, v195
	v_and_b32_e32 v197, 0xffff0000, v197
	v_and_b32_e32 v199, 0xffff0000, v199
	v_or_b32_sdwa v208, v193, v192 dst_sel:DWORD dst_unused:UNUSED_PAD src0_sel:DWORD src1_sel:WORD_1
	v_or_b32_sdwa v209, v195, v194 dst_sel:DWORD dst_unused:UNUSED_PAD src0_sel:DWORD src1_sel:WORD_1
	v_or_b32_sdwa v210, v197, v196 dst_sel:DWORD dst_unused:UNUSED_PAD src0_sel:DWORD src1_sel:WORD_1
	v_or_b32_sdwa v211, v199, v198 dst_sel:DWORD dst_unused:UNUSED_PAD src0_sel:DWORD src1_sel:WORD_1
	s_nop 1
	v_permlane16_swap_b32_e32 v208, v210
	v_permlane16_swap_b32_e32 v209, v211
	global_store_dwordx4 v219, v[208:211], s[84:85]
	v_and_b32_sdwa v200, v56, v108 dst_sel:DWORD dst_unused:UNUSED_PAD src0_sel:WORD_1 src1_sel:DWORD
	v_and_b32_sdwa v201, v57, v108 dst_sel:DWORD dst_unused:UNUSED_PAD src0_sel:WORD_1 src1_sel:DWORD
	v_and_b32_sdwa v202, v58, v108 dst_sel:DWORD dst_unused:UNUSED_PAD src0_sel:WORD_1 src1_sel:DWORD
	v_and_b32_sdwa v203, v59, v108 dst_sel:DWORD dst_unused:UNUSED_PAD src0_sel:WORD_1 src1_sel:DWORD
	v_and_b32_sdwa v204, v60, v108 dst_sel:DWORD dst_unused:UNUSED_PAD src0_sel:WORD_1 src1_sel:DWORD
	v_and_b32_sdwa v205, v61, v108 dst_sel:DWORD dst_unused:UNUSED_PAD src0_sel:WORD_1 src1_sel:DWORD
	v_and_b32_sdwa v206, v62, v108 dst_sel:DWORD dst_unused:UNUSED_PAD src0_sel:WORD_1 src1_sel:DWORD
	v_and_b32_sdwa v207, v63, v108 dst_sel:DWORD dst_unused:UNUSED_PAD src0_sel:WORD_1 src1_sel:DWORD
	v_add3_u32 v192, v56, v200, s66
	v_add3_u32 v193, v57, v201, s66
	v_add3_u32 v194, v58, v202, s66
	v_add3_u32 v195, v59, v203, s66
	v_add3_u32 v196, v60, v204, s66
	v_add3_u32 v197, v61, v205, s66
	v_add3_u32 v198, v62, v206, s66
	v_add3_u32 v199, v63, v207, s66
	v_and_b32_e32 v193, 0xffff0000, v193
	v_and_b32_e32 v195, 0xffff0000, v195
	v_and_b32_e32 v197, 0xffff0000, v197
	v_and_b32_e32 v199, 0xffff0000, v199
	v_or_b32_sdwa v212, v193, v192 dst_sel:DWORD dst_unused:UNUSED_PAD src0_sel:DWORD src1_sel:WORD_1
	v_or_b32_sdwa v213, v195, v194 dst_sel:DWORD dst_unused:UNUSED_PAD src0_sel:DWORD src1_sel:WORD_1
	v_or_b32_sdwa v214, v197, v196 dst_sel:DWORD dst_unused:UNUSED_PAD src0_sel:DWORD src1_sel:WORD_1
	v_or_b32_sdwa v215, v199, v198 dst_sel:DWORD dst_unused:UNUSED_PAD src0_sel:DWORD src1_sel:WORD_1
	s_nop 1
	v_permlane16_swap_b32_e32 v212, v214
	v_permlane16_swap_b32_e32 v213, v215
	global_store_dwordx4 v219, v[212:215], s[84:85] offset:64
	s_cmp_eq_u32 s95, 1
	s_cbranch_scc0 .Lgp9_single
	s_load_dwordx2 s[84:85], s[0:1], 0xa0
	v_lshrrev_b32_e32 v220, 1, v168
	v_and_b32_e32 v220, 0x1c0, v220
	v_and_b32_e32 v221, 15, v168
	v_or_b32_e32 v220, v220, v221
	v_lshl_add_u32 v220, s50, 7, v220
	v_lshlrev_b32_e32 v220, 12, v220
	v_bfe_u32 v221, v168, 4, 2
	v_lshlrev_b32_e32 v217, 3, v221
	v_and_b32_e32 v221, 1, v221
	v_mul_u32_u24_e32 v221, 24, v221
	v_add3_u32 v220, v220, v221, v217
	v_bfe_u32 v221, v168, 6, 1
	s_lshl_b32 s87, s83, 8
	v_lshl_add_u32 v216, v221, 7, v220
	v_add_u32_e32 v216, s87, v216
	v_add_u32_e32 v217, 0x10000, v216
	v_add_u32_e32 v218, 0x20000, v216
	v_add_u32_e32 v219, 0x30000, v216
	s_waitcnt lgkmcnt(0)
	v_and_b32_sdwa v200, v116, v108 dst_sel:DWORD dst_unused:UNUSED_PAD src0_sel:WORD_1 src1_sel:DWORD
	v_and_b32_sdwa v201, v117, v108 dst_sel:DWORD dst_unused:UNUSED_PAD src0_sel:WORD_1 src1_sel:DWORD
	v_and_b32_sdwa v202, v118, v108 dst_sel:DWORD dst_unused:UNUSED_PAD src0_sel:WORD_1 src1_sel:DWORD
	v_and_b32_sdwa v203, v119, v108 dst_sel:DWORD dst_unused:UNUSED_PAD src0_sel:WORD_1 src1_sel:DWORD
	v_and_b32_sdwa v204, v120, v108 dst_sel:DWORD dst_unused:UNUSED_PAD src0_sel:WORD_1 src1_sel:DWORD
	v_and_b32_sdwa v205, v121, v108 dst_sel:DWORD dst_unused:UNUSED_PAD src0_sel:WORD_1 src1_sel:DWORD
	v_and_b32_sdwa v206, v122, v108 dst_sel:DWORD dst_unused:UNUSED_PAD src0_sel:WORD_1 src1_sel:DWORD
	v_and_b32_sdwa v207, v123, v108 dst_sel:DWORD dst_unused:UNUSED_PAD src0_sel:WORD_1 src1_sel:DWORD
	v_add3_u32 v192, v116, v200, s66
	v_add3_u32 v193, v117, v201, s66
	v_add3_u32 v194, v118, v202, s66
	v_add3_u32 v195, v119, v203, s66
	v_add3_u32 v196, v120, v204, s66
	v_add3_u32 v197, v121, v205, s66
	v_add3_u32 v198, v122, v206, s66
	v_add3_u32 v199, v123, v207, s66
	v_and_b32_e32 v193, 0xffff0000, v193
	v_and_b32_e32 v195, 0xffff0000, v195
	v_and_b32_e32 v197, 0xffff0000, v197
	v_and_b32_e32 v199, 0xffff0000, v199
	v_or_b32_sdwa v208, v193, v192 dst_sel:DWORD dst_unused:UNUSED_PAD src0_sel:DWORD src1_sel:WORD_1
	v_or_b32_sdwa v209, v195, v194 dst_sel:DWORD dst_unused:UNUSED_PAD src0_sel:DWORD src1_sel:WORD_1
	v_or_b32_sdwa v210, v197, v196 dst_sel:DWORD dst_unused:UNUSED_PAD src0_sel:DWORD src1_sel:WORD_1
	v_or_b32_sdwa v211, v199, v198 dst_sel:DWORD dst_unused:UNUSED_PAD src0_sel:DWORD src1_sel:WORD_1
	s_nop 1
	v_permlane16_swap_b32_e32 v208, v210
	v_permlane16_swap_b32_e32 v209, v211
	global_store_dwordx4 v216, v[208:211], s[84:85]
	v_and_b32_sdwa v200, v124, v108 dst_sel:DWORD dst_unused:UNUSED_PAD src0_sel:WORD_1 src1_sel:DWORD
	v_and_b32_sdwa v201, v125, v108 dst_sel:DWORD dst_unused:UNUSED_PAD src0_sel:WORD_1 src1_sel:DWORD
	v_and_b32_sdwa v202, v126, v108 dst_sel:DWORD dst_unused:UNUSED_PAD src0_sel:WORD_1 src1_sel:DWORD
	v_and_b32_sdwa v203, v127, v108 dst_sel:DWORD dst_unused:UNUSED_PAD src0_sel:WORD_1 src1_sel:DWORD
	v_and_b32_sdwa v204, v128, v108 dst_sel:DWORD dst_unused:UNUSED_PAD src0_sel:WORD_1 src1_sel:DWORD
	v_and_b32_sdwa v205, v129, v108 dst_sel:DWORD dst_unused:UNUSED_PAD src0_sel:WORD_1 src1_sel:DWORD
	v_and_b32_sdwa v206, v130, v108 dst_sel:DWORD dst_unused:UNUSED_PAD src0_sel:WORD_1 src1_sel:DWORD
	v_and_b32_sdwa v207, v131, v108 dst_sel:DWORD dst_unused:UNUSED_PAD src0_sel:WORD_1 src1_sel:DWORD
	v_add3_u32 v192, v124, v200, s66
	v_add3_u32 v193, v125, v201, s66
	v_add3_u32 v194, v126, v202, s66
	v_add3_u32 v195, v127, v203, s66
	v_add3_u32 v196, v128, v204, s66
	v_add3_u32 v197, v129, v205, s66
	v_add3_u32 v198, v130, v206, s66
	v_add3_u32 v199, v131, v207, s66
	v_and_b32_e32 v193, 0xffff0000, v193
	v_and_b32_e32 v195, 0xffff0000, v195
	v_and_b32_e32 v197, 0xffff0000, v197
	v_and_b32_e32 v199, 0xffff0000, v199
	v_or_b32_sdwa v212, v193, v192 dst_sel:DWORD dst_unused:UNUSED_PAD src0_sel:DWORD src1_sel:WORD_1
	v_or_b32_sdwa v213, v195, v194 dst_sel:DWORD dst_unused:UNUSED_PAD src0_sel:DWORD src1_sel:WORD_1
	v_or_b32_sdwa v214, v197, v196 dst_sel:DWORD dst_unused:UNUSED_PAD src0_sel:DWORD src1_sel:WORD_1
	v_or_b32_sdwa v215, v199, v198 dst_sel:DWORD dst_unused:UNUSED_PAD src0_sel:DWORD src1_sel:WORD_1
	s_nop 1
	v_permlane16_swap_b32_e32 v212, v214
	v_permlane16_swap_b32_e32 v213, v215
	global_store_dwordx4 v216, v[212:215], s[84:85] offset:64
	v_and_b32_sdwa v200, v132, v108 dst_sel:DWORD dst_unused:UNUSED_PAD src0_sel:WORD_1 src1_sel:DWORD
	v_and_b32_sdwa v201, v133, v108 dst_sel:DWORD dst_unused:UNUSED_PAD src0_sel:WORD_1 src1_sel:DWORD
	v_and_b32_sdwa v202, v134, v108 dst_sel:DWORD dst_unused:UNUSED_PAD src0_sel:WORD_1 src1_sel:DWORD
	v_and_b32_sdwa v203, v135, v108 dst_sel:DWORD dst_unused:UNUSED_PAD src0_sel:WORD_1 src1_sel:DWORD
	v_and_b32_sdwa v204, v136, v108 dst_sel:DWORD dst_unused:UNUSED_PAD src0_sel:WORD_1 src1_sel:DWORD
	v_and_b32_sdwa v205, v137, v108 dst_sel:DWORD dst_unused:UNUSED_PAD src0_sel:WORD_1 src1_sel:DWORD
	v_and_b32_sdwa v206, v138, v108 dst_sel:DWORD dst_unused:UNUSED_PAD src0_sel:WORD_1 src1_sel:DWORD
	v_and_b32_sdwa v207, v139, v108 dst_sel:DWORD dst_unused:UNUSED_PAD src0_sel:WORD_1 src1_sel:DWORD
	v_add3_u32 v192, v132, v200, s66
	v_add3_u32 v193, v133, v201, s66
	v_add3_u32 v194, v134, v202, s66
	v_add3_u32 v195, v135, v203, s66
	v_add3_u32 v196, v136, v204, s66
	v_add3_u32 v197, v137, v205, s66
	v_add3_u32 v198, v138, v206, s66
	v_add3_u32 v199, v139, v207, s66
	v_and_b32_e32 v193, 0xffff0000, v193
	v_and_b32_e32 v195, 0xffff0000, v195
	v_and_b32_e32 v197, 0xffff0000, v197
	v_and_b32_e32 v199, 0xffff0000, v199
	v_or_b32_sdwa v208, v193, v192 dst_sel:DWORD dst_unused:UNUSED_PAD src0_sel:DWORD src1_sel:WORD_1
	v_or_b32_sdwa v209, v195, v194 dst_sel:DWORD dst_unused:UNUSED_PAD src0_sel:DWORD src1_sel:WORD_1
	v_or_b32_sdwa v210, v197, v196 dst_sel:DWORD dst_unused:UNUSED_PAD src0_sel:DWORD src1_sel:WORD_1
	v_or_b32_sdwa v211, v199, v198 dst_sel:DWORD dst_unused:UNUSED_PAD src0_sel:DWORD src1_sel:WORD_1
	s_nop 1
	v_permlane16_swap_b32_e32 v208, v210
	v_permlane16_swap_b32_e32 v209, v211
	global_store_dwordx4 v217, v[208:211], s[84:85]
	v_and_b32_sdwa v200, v140, v108 dst_sel:DWORD dst_unused:UNUSED_PAD src0_sel:WORD_1 src1_sel:DWORD
	v_and_b32_sdwa v201, v141, v108 dst_sel:DWORD dst_unused:UNUSED_PAD src0_sel:WORD_1 src1_sel:DWORD
	v_and_b32_sdwa v202, v142, v108 dst_sel:DWORD dst_unused:UNUSED_PAD src0_sel:WORD_1 src1_sel:DWORD
	v_and_b32_sdwa v203, v143, v108 dst_sel:DWORD dst_unused:UNUSED_PAD src0_sel:WORD_1 src1_sel:DWORD
	v_and_b32_sdwa v204, v148, v108 dst_sel:DWORD dst_unused:UNUSED_PAD src0_sel:WORD_1 src1_sel:DWORD
	v_and_b32_sdwa v205, v149, v108 dst_sel:DWORD dst_unused:UNUSED_PAD src0_sel:WORD_1 src1_sel:DWORD
	v_and_b32_sdwa v206, v150, v108 dst_sel:DWORD dst_unused:UNUSED_PAD src0_sel:WORD_1 src1_sel:DWORD
	v_and_b32_sdwa v207, v151, v108 dst_sel:DWORD dst_unused:UNUSED_PAD src0_sel:WORD_1 src1_sel:DWORD
	v_add3_u32 v192, v140, v200, s66
	v_add3_u32 v193, v141, v201, s66
	v_add3_u32 v194, v142, v202, s66
	v_add3_u32 v195, v143, v203, s66
	v_add3_u32 v196, v148, v204, s66
	v_add3_u32 v197, v149, v205, s66
	v_add3_u32 v198, v150, v206, s66
	v_add3_u32 v199, v151, v207, s66
	v_and_b32_e32 v193, 0xffff0000, v193
	v_and_b32_e32 v195, 0xffff0000, v195
	v_and_b32_e32 v197, 0xffff0000, v197
	v_and_b32_e32 v199, 0xffff0000, v199
	v_or_b32_sdwa v212, v193, v192 dst_sel:DWORD dst_unused:UNUSED_PAD src0_sel:DWORD src1_sel:WORD_1
	v_or_b32_sdwa v213, v195, v194 dst_sel:DWORD dst_unused:UNUSED_PAD src0_sel:DWORD src1_sel:WORD_1
	v_or_b32_sdwa v214, v197, v196 dst_sel:DWORD dst_unused:UNUSED_PAD src0_sel:DWORD src1_sel:WORD_1
	v_or_b32_sdwa v215, v199, v198 dst_sel:DWORD dst_unused:UNUSED_PAD src0_sel:DWORD src1_sel:WORD_1
	s_nop 1
	v_permlane16_swap_b32_e32 v212, v214
	v_permlane16_swap_b32_e32 v213, v215
	global_store_dwordx4 v217, v[212:215], s[84:85] offset:64
	v_and_b32_sdwa v200, v152, v108 dst_sel:DWORD dst_unused:UNUSED_PAD src0_sel:WORD_1 src1_sel:DWORD
	v_and_b32_sdwa v201, v153, v108 dst_sel:DWORD dst_unused:UNUSED_PAD src0_sel:WORD_1 src1_sel:DWORD
	v_and_b32_sdwa v202, v154, v108 dst_sel:DWORD dst_unused:UNUSED_PAD src0_sel:WORD_1 src1_sel:DWORD
	v_and_b32_sdwa v203, v155, v108 dst_sel:DWORD dst_unused:UNUSED_PAD src0_sel:WORD_1 src1_sel:DWORD
	v_and_b32_sdwa v204, v156, v108 dst_sel:DWORD dst_unused:UNUSED_PAD src0_sel:WORD_1 src1_sel:DWORD
	v_and_b32_sdwa v205, v157, v108 dst_sel:DWORD dst_unused:UNUSED_PAD src0_sel:WORD_1 src1_sel:DWORD
	v_and_b32_sdwa v206, v158, v108 dst_sel:DWORD dst_unused:UNUSED_PAD src0_sel:WORD_1 src1_sel:DWORD
	v_and_b32_sdwa v207, v159, v108 dst_sel:DWORD dst_unused:UNUSED_PAD src0_sel:WORD_1 src1_sel:DWORD
	v_add3_u32 v192, v152, v200, s66
	v_add3_u32 v193, v153, v201, s66
	v_add3_u32 v194, v154, v202, s66
	v_add3_u32 v195, v155, v203, s66
	v_add3_u32 v196, v156, v204, s66
	v_add3_u32 v197, v157, v205, s66
	v_add3_u32 v198, v158, v206, s66
	v_add3_u32 v199, v159, v207, s66
	v_and_b32_e32 v193, 0xffff0000, v193
	v_and_b32_e32 v195, 0xffff0000, v195
	v_and_b32_e32 v197, 0xffff0000, v197
	v_and_b32_e32 v199, 0xffff0000, v199
	v_or_b32_sdwa v208, v193, v192 dst_sel:DWORD dst_unused:UNUSED_PAD src0_sel:DWORD src1_sel:WORD_1
	v_or_b32_sdwa v209, v195, v194 dst_sel:DWORD dst_unused:UNUSED_PAD src0_sel:DWORD src1_sel:WORD_1
	v_or_b32_sdwa v210, v197, v196 dst_sel:DWORD dst_unused:UNUSED_PAD src0_sel:DWORD src1_sel:WORD_1
	v_or_b32_sdwa v211, v199, v198 dst_sel:DWORD dst_unused:UNUSED_PAD src0_sel:DWORD src1_sel:WORD_1
	s_nop 1
	v_permlane16_swap_b32_e32 v208, v210
	v_permlane16_swap_b32_e32 v209, v211
	global_store_dwordx4 v218, v[208:211], s[84:85]
	v_and_b32_sdwa v200, v160, v108 dst_sel:DWORD dst_unused:UNUSED_PAD src0_sel:WORD_1 src1_sel:DWORD
	v_and_b32_sdwa v201, v161, v108 dst_sel:DWORD dst_unused:UNUSED_PAD src0_sel:WORD_1 src1_sel:DWORD
	v_and_b32_sdwa v202, v162, v108 dst_sel:DWORD dst_unused:UNUSED_PAD src0_sel:WORD_1 src1_sel:DWORD
	v_and_b32_sdwa v203, v163, v108 dst_sel:DWORD dst_unused:UNUSED_PAD src0_sel:WORD_1 src1_sel:DWORD
	v_and_b32_sdwa v204, v172, v108 dst_sel:DWORD dst_unused:UNUSED_PAD src0_sel:WORD_1 src1_sel:DWORD
	v_and_b32_sdwa v205, v173, v108 dst_sel:DWORD dst_unused:UNUSED_PAD src0_sel:WORD_1 src1_sel:DWORD
	v_and_b32_sdwa v206, v174, v108 dst_sel:DWORD dst_unused:UNUSED_PAD src0_sel:WORD_1 src1_sel:DWORD
	v_and_b32_sdwa v207, v175, v108 dst_sel:DWORD dst_unused:UNUSED_PAD src0_sel:WORD_1 src1_sel:DWORD
	v_add3_u32 v192, v160, v200, s66
	v_add3_u32 v193, v161, v201, s66
	v_add3_u32 v194, v162, v202, s66
	v_add3_u32 v195, v163, v203, s66
	v_add3_u32 v196, v172, v204, s66
	v_add3_u32 v197, v173, v205, s66
	v_add3_u32 v198, v174, v206, s66
	v_add3_u32 v199, v175, v207, s66
	v_and_b32_e32 v193, 0xffff0000, v193
	v_and_b32_e32 v195, 0xffff0000, v195
	v_and_b32_e32 v197, 0xffff0000, v197
	v_and_b32_e32 v199, 0xffff0000, v199
	v_or_b32_sdwa v212, v193, v192 dst_sel:DWORD dst_unused:UNUSED_PAD src0_sel:DWORD src1_sel:WORD_1
	v_or_b32_sdwa v213, v195, v194 dst_sel:DWORD dst_unused:UNUSED_PAD src0_sel:DWORD src1_sel:WORD_1
	v_or_b32_sdwa v214, v197, v196 dst_sel:DWORD dst_unused:UNUSED_PAD src0_sel:DWORD src1_sel:WORD_1
	v_or_b32_sdwa v215, v199, v198 dst_sel:DWORD dst_unused:UNUSED_PAD src0_sel:DWORD src1_sel:WORD_1
	s_nop 1
	v_permlane16_swap_b32_e32 v212, v214
	v_permlane16_swap_b32_e32 v213, v215
	global_store_dwordx4 v218, v[212:215], s[84:85] offset:64
	v_and_b32_sdwa v200, v176, v108 dst_sel:DWORD dst_unused:UNUSED_PAD src0_sel:WORD_1 src1_sel:DWORD
	v_and_b32_sdwa v201, v177, v108 dst_sel:DWORD dst_unused:UNUSED_PAD src0_sel:WORD_1 src1_sel:DWORD
	v_and_b32_sdwa v202, v178, v108 dst_sel:DWORD dst_unused:UNUSED_PAD src0_sel:WORD_1 src1_sel:DWORD
	v_and_b32_sdwa v203, v179, v108 dst_sel:DWORD dst_unused:UNUSED_PAD src0_sel:WORD_1 src1_sel:DWORD
	v_and_b32_sdwa v204, v180, v108 dst_sel:DWORD dst_unused:UNUSED_PAD src0_sel:WORD_1 src1_sel:DWORD
	v_and_b32_sdwa v205, v181, v108 dst_sel:DWORD dst_unused:UNUSED_PAD src0_sel:WORD_1 src1_sel:DWORD
	v_and_b32_sdwa v206, v182, v108 dst_sel:DWORD dst_unused:UNUSED_PAD src0_sel:WORD_1 src1_sel:DWORD
	v_and_b32_sdwa v207, v183, v108 dst_sel:DWORD dst_unused:UNUSED_PAD src0_sel:WORD_1 src1_sel:DWORD
	v_add3_u32 v192, v176, v200, s66
	v_add3_u32 v193, v177, v201, s66
	v_add3_u32 v194, v178, v202, s66
	v_add3_u32 v195, v179, v203, s66
	v_add3_u32 v196, v180, v204, s66
	v_add3_u32 v197, v181, v205, s66
	v_add3_u32 v198, v182, v206, s66
	v_add3_u32 v199, v183, v207, s66
	v_and_b32_e32 v193, 0xffff0000, v193
	v_and_b32_e32 v195, 0xffff0000, v195
	v_and_b32_e32 v197, 0xffff0000, v197
	v_and_b32_e32 v199, 0xffff0000, v199
	v_or_b32_sdwa v208, v193, v192 dst_sel:DWORD dst_unused:UNUSED_PAD src0_sel:DWORD src1_sel:WORD_1
	v_or_b32_sdwa v209, v195, v194 dst_sel:DWORD dst_unused:UNUSED_PAD src0_sel:DWORD src1_sel:WORD_1
	v_or_b32_sdwa v210, v197, v196 dst_sel:DWORD dst_unused:UNUSED_PAD src0_sel:DWORD src1_sel:WORD_1
	v_or_b32_sdwa v211, v199, v198 dst_sel:DWORD dst_unused:UNUSED_PAD src0_sel:DWORD src1_sel:WORD_1
	s_nop 1
	v_permlane16_swap_b32_e32 v208, v210
	v_permlane16_swap_b32_e32 v209, v211
	global_store_dwordx4 v219, v[208:211], s[84:85]
	v_and_b32_sdwa v200, v184, v108 dst_sel:DWORD dst_unused:UNUSED_PAD src0_sel:WORD_1 src1_sel:DWORD
	v_and_b32_sdwa v201, v185, v108 dst_sel:DWORD dst_unused:UNUSED_PAD src0_sel:WORD_1 src1_sel:DWORD
	v_and_b32_sdwa v202, v186, v108 dst_sel:DWORD dst_unused:UNUSED_PAD src0_sel:WORD_1 src1_sel:DWORD
	v_and_b32_sdwa v203, v187, v108 dst_sel:DWORD dst_unused:UNUSED_PAD src0_sel:WORD_1 src1_sel:DWORD
	v_and_b32_sdwa v204, v188, v108 dst_sel:DWORD dst_unused:UNUSED_PAD src0_sel:WORD_1 src1_sel:DWORD
	v_and_b32_sdwa v205, v189, v108 dst_sel:DWORD dst_unused:UNUSED_PAD src0_sel:WORD_1 src1_sel:DWORD
	v_and_b32_sdwa v206, v190, v108 dst_sel:DWORD dst_unused:UNUSED_PAD src0_sel:WORD_1 src1_sel:DWORD
	v_and_b32_sdwa v207, v191, v108 dst_sel:DWORD dst_unused:UNUSED_PAD src0_sel:WORD_1 src1_sel:DWORD
	v_add3_u32 v192, v184, v200, s66
	v_add3_u32 v193, v185, v201, s66
	v_add3_u32 v194, v186, v202, s66
	v_add3_u32 v195, v187, v203, s66
	v_add3_u32 v196, v188, v204, s66
	v_add3_u32 v197, v189, v205, s66
	v_add3_u32 v198, v190, v206, s66
	v_add3_u32 v199, v191, v207, s66
	v_and_b32_e32 v193, 0xffff0000, v193
	v_and_b32_e32 v195, 0xffff0000, v195
	v_and_b32_e32 v197, 0xffff0000, v197
	v_and_b32_e32 v199, 0xffff0000, v199
	v_or_b32_sdwa v212, v193, v192 dst_sel:DWORD dst_unused:UNUSED_PAD src0_sel:DWORD src1_sel:WORD_1
	v_or_b32_sdwa v213, v195, v194 dst_sel:DWORD dst_unused:UNUSED_PAD src0_sel:DWORD src1_sel:WORD_1
	v_or_b32_sdwa v214, v197, v196 dst_sel:DWORD dst_unused:UNUSED_PAD src0_sel:DWORD src1_sel:WORD_1
	v_or_b32_sdwa v215, v199, v198 dst_sel:DWORD dst_unused:UNUSED_PAD src0_sel:DWORD src1_sel:WORD_1
	s_nop 1
	v_permlane16_swap_b32_e32 v212, v214
	v_permlane16_swap_b32_e32 v213, v215
	global_store_dwordx4 v219, v[212:215], s[84:85] offset:64
	s_add_i32 s61, s61, s60
